# differential-attention loop: redundant max(x,x) canonicalisations in the running-max chain removed (six instructions per loop body)
# baseline (speedup 1.0000x reference)
.LBB0_1085:
	ds_read_b128 v[64:67], v181 offset:40960
	ds_read_b128 v[68:71], v181 offset:45056
	v_exp_f32_e32 v194, v136
	v_pk_add_f32 v[190:191], v[144:145], v[146:147]
	v_pk_add_f32 v[190:191], v[190:191], v[148:149]
	s_waitcnt lgkmcnt(1)
	v_mfma_f32_32x32x16_bf16 v[80:95], v[64:67], v[108:111], 0
	v_pk_add_f32 v[190:191], v[190:191], v[150:151]
	v_pk_add_f32 v[190:191], v[190:191], v[160:161]
	ds_read_b128 v[198:201], v187 offset:40960
	ds_read_b128 v[202:205], v187 offset:45056
	v_pk_add_f32 v[190:191], v[190:191], v[162:163]
	v_pk_add_f32 v[190:191], v[190:191], v[142:143]
	s_waitcnt lgkmcnt(2)
	v_mfma_f32_32x32x16_bf16 v[64:79], v[68:71], v[108:111], 0
	v_exp_f32_e32 v141, v138
	v_exp_f32_e32 v192, v139
	s_waitcnt lgkmcnt(1)
	v_mfma_f32_32x32x16_bf16 v[80:95], v[198:201], v[100:103], v[80:95]
	v_exp_f32_e32 v195, v137
	v_exp_f32_e32 v132, v132
	v_exp_f32_e32 v133, v133
	v_pk_add_f32 v[190:191], v[190:191], v[192:193]
	s_waitcnt lgkmcnt(0)
	v_mfma_f32_32x32x16_bf16 v[64:79], v[202:205], v[100:103], v[64:79]
	ds_read_b128 v[198:201], v188 offset:40960
	ds_read_b128 v[202:205], v188 offset:45056
	v_exp_f32_e32 v128, v128
	v_exp_f32_e32 v129, v129
	v_pk_add_f32 v[190:191], v[190:191], v[194:195]
	v_exp_f32_e32 v126, v126
	s_waitcnt lgkmcnt(1)
	v_mfma_f32_32x32x16_bf16 v[80:95], v[198:201], v[96:99], v[80:95]
	v_pk_add_f32 v[190:191], v[190:191], v[132:133]
	v_exp_f32_e32 v127, v127
	v_exp_f32_e32 v134, v134
	v_pk_add_f32 v[190:191], v[190:191], v[128:129]
	v_exp_f32_e32 v135, v135
	s_waitcnt lgkmcnt(0)
	v_mfma_f32_32x32x16_bf16 v[64:79], v[202:205], v[96:99], v[64:79]
	ds_read_b128 v[198:201], v176 offset:40960
	ds_read_b128 v[202:205], v176 offset:45056
	v_exp_f32_e32 v130, v130
	v_pk_add_f32 v[190:191], v[190:191], v[126:127]
	v_exp_f32_e32 v131, v131
	v_exp_f32_e32 v124, v124
	v_pk_add_f32 v[190:191], v[190:191], v[134:135]
	s_waitcnt lgkmcnt(1)
	v_mfma_f32_32x32x16_bf16 v[80:95], v[198:201], v[104:107], v[80:95]
	v_exp_f32_e32 v125, v125
	v_pk_add_f32 v[190:191], v[190:191], v[130:131]
	v_add_f32_e32 v136, v196, v141
	v_pk_add_f32 v[190:191], v[190:191], v[124:125]
	v_add_f32_e32 v190, v190, v191
	v_add_f32_e32 v190, v136, v190
	v_mov_b32_e32 v191, v190
	s_waitcnt lgkmcnt(0)
	v_mfma_f32_32x32x16_bf16 v[64:79], v[202:205], v[104:107], v[64:79]
	v_cvt_pk_bf16_f32 v136, v144, v146
	v_cvt_pk_bf16_f32 v138, v160, v162
	v_cvt_pk_bf16_f32 v142, v142, v143
	v_cvt_pk_bf16_f32 v143, v145, v147
	v_cvt_pk_bf16_f32 v146, v141, v192
	v_cvt_pk_bf16_f32 v147, v194, v195
	v_cvt_pk_bf16_f32 v192, v126, v127
	v_cvt_pk_bf16_f32 v194, v130, v131
	v_permlane32_swap_b32_e32 v190, v191
	v_cvt_pk_bf16_f32 v137, v148, v150
	v_cvt_pk_bf16_f32 v139, v163, v196
	v_permlane32_swap_b32_e32 v136, v138
	v_cvt_pk_bf16_f32 v144, v149, v151
	v_cvt_pk_bf16_f32 v145, v161, v193
	v_cvt_pk_bf16_f32 v148, v132, v133
	v_cvt_pk_bf16_f32 v149, v128, v129
	v_cvt_pk_bf16_f32 v193, v134, v135
	v_cvt_pk_bf16_f32 v195, v124, v125
	v_permlane32_swap_b32_e32 v192, v194
	v_permlane32_swap_b32_e32 v137, v139
	v_permlane32_swap_b32_e32 v142, v144
	v_permlane32_swap_b32_e32 v143, v145
	v_permlane32_swap_b32_e32 v146, v148
	v_permlane32_swap_b32_e32 v147, v149
	v_permlane32_swap_b32_e32 v193, v195
	v_lshl_add_u64 v[160:161], v[158:159], 0, s[30:31]
	v_add_co_u32_e32 v124, vcc, s39, v160
	s_mov_b32 s4, 0x186c0000
	s_nop 0
	v_addc_co_u32_e32 v125, vcc, 0, v161, vcc
	v_add_co_u32_e32 v128, vcc, s4, v160
	v_lshl_add_u64 v[162:163], v[156:157], 0, s[30:31]
	s_nop 0
	v_addc_co_u32_e32 v129, vcc, 0, v161, vcc
	v_add_co_u32_e32 v132, vcc, s39, v162
	global_load_dwordx4 v[124:127], v[124:125], off offset:3072
	s_nop 0
	global_load_dwordx4 v[128:131], v[128:129], off offset:3072
	v_addc_co_u32_e32 v133, vcc, 0, v163, vcc
	global_load_dwordx4 v[132:135], v[132:133], off offset:1536
	ds_read_b64_tr_b16 v[196:197], v175 offset:0
	ds_read_b64_tr_b16 v[198:199], v175 offset:0x800
	ds_read_b64_tr_b16 v[200:201], v175 offset:0x1000
	ds_read_b64_tr_b16 v[202:203], v175 offset:0x1800
	ds_read_b64_tr_b16 v[204:205], v175 offset:0x2000
	ds_read_b64_tr_b16 v[206:207], v175 offset:0x2800
	ds_read_b64_tr_b16 v[208:209], v175 offset:0x3000
	ds_read_b64_tr_b16 v[210:211], v175 offset:0x3800
	s_waitcnt lgkmcnt(0)
	s_nop 0
	v_mfma_f32_32x32x16_bf16 v[0:15], v[136:139], v[196:199], v[0:15]
	ds_read_b64_tr_b16 v[196:197], v175 offset:0x200
	ds_read_b64_tr_b16 v[198:199], v175 offset:0xa00
	v_mfma_f32_32x32x16_bf16 v[0:15], v[142:145], v[200:203], v[0:15]
	ds_read_b64_tr_b16 v[200:201], v175 offset:0x1200
	ds_read_b64_tr_b16 v[202:203], v175 offset:0x1a00
	v_mfma_f32_32x32x16_bf16 v[0:15], v[146:149], v[204:207], v[0:15]
	ds_read_b64_tr_b16 v[204:205], v175 offset:0x2200
	ds_read_b64_tr_b16 v[206:207], v175 offset:0x2a00
	v_mfma_f32_32x32x16_bf16 v[0:15], v[192:195], v[208:211], v[0:15]
	ds_read_b64_tr_b16 v[208:209], v175 offset:0x3200
	ds_read_b64_tr_b16 v[210:211], v175 offset:0x3a00
	s_waitcnt lgkmcnt(0)
	v_mfma_f32_32x32x16_bf16 v[48:63], v[136:139], v[196:199], v[48:63]
	ds_read_b64_tr_b16 v[196:197], v175 offset:0x400
	ds_read_b64_tr_b16 v[198:199], v175 offset:0xc00
	v_mfma_f32_32x32x16_bf16 v[48:63], v[142:145], v[200:203], v[48:63]
	ds_read_b64_tr_b16 v[200:201], v175 offset:0x1400
	ds_read_b64_tr_b16 v[202:203], v175 offset:0x1c00
	v_mfma_f32_32x32x16_bf16 v[48:63], v[146:149], v[204:207], v[48:63]
	ds_read_b64_tr_b16 v[204:205], v175 offset:0x2400
	ds_read_b64_tr_b16 v[206:207], v175 offset:0x2c00
	v_mfma_f32_32x32x16_bf16 v[48:63], v[192:195], v[208:211], v[48:63]
	ds_read_b64_tr_b16 v[208:209], v175 offset:0x3400
	ds_read_b64_tr_b16 v[210:211], v175 offset:0x3c00
	s_waitcnt lgkmcnt(0)
	v_mfma_f32_32x32x16_bf16 v[32:47], v[136:139], v[196:199], v[32:47]
	ds_read_b64_tr_b16 v[196:197], v175 offset:0x600
	ds_read_b64_tr_b16 v[198:199], v175 offset:0xe00
	v_mfma_f32_32x32x16_bf16 v[32:47], v[142:145], v[200:203], v[32:47]
	ds_read_b64_tr_b16 v[200:201], v175 offset:0x1600
	ds_read_b64_tr_b16 v[202:203], v175 offset:0x1e00
	v_mfma_f32_32x32x16_bf16 v[32:47], v[146:149], v[204:207], v[32:47]
	ds_read_b64_tr_b16 v[204:205], v175 offset:0x2600
	ds_read_b64_tr_b16 v[206:207], v175 offset:0x2e00
	v_mfma_f32_32x32x16_bf16 v[32:47], v[192:195], v[208:211], v[32:47]
	ds_read_b64_tr_b16 v[208:209], v175 offset:0x3600
	ds_read_b64_tr_b16 v[210:211], v175 offset:0x3e00
	s_waitcnt lgkmcnt(0)
	v_mfma_f32_32x32x16_bf16 v[16:31], v[136:139], v[196:199], v[16:31]
	v_max_f32_e32 v136, v80, v81
	v_max3_f32 v136, v136, v82, v83
	v_max3_f32 v136, v136, v84, v85
	v_max3_f32 v136, v136, v86, v87
	v_max3_f32 v136, v136, v88, v89
	v_max3_f32 v136, v136, v90, v91
	v_max3_f32 v136, v136, v92, v93
	v_mfma_f32_32x32x16_bf16 v[16:31], v[142:145], v[200:203], v[16:31]
	v_max3_f32 v136, v136, v94, v95
	v_max3_f32 v136, v136, v64, v65
	v_max3_f32 v136, v136, v66, v67
	v_max3_f32 v136, v136, v68, v69
	v_max3_f32 v136, v136, v70, v71
	v_max3_f32 v136, v136, v72, v73
	v_max3_f32 v136, v136, v74, v75
	v_max3_f32 v136, v136, v76, v77
	v_mfma_f32_32x32x16_bf16 v[16:31], v[146:149], v[204:207], v[16:31]
	v_max3_f32 v136, v136, v78, v79
	v_mov_b32_e32 v137, v136
	s_nop 1
	v_permlane32_swap_b32_e32 v136, v137
	v_max_f32_e32 v137, v137, v137
	v_max_f32_e32 v136, v136, v136
	v_max_f32_e32 v136, v136, v137
	v_sub_f32_e32 v137, v136, v140
	v_cmp_ge_f32_e32 vcc, s38, v137
	v_max_f32_e32 v136, v140, v136
	v_mfma_f32_32x32x16_bf16 v[16:31], v[192:195], v[208:211], v[16:31]
	v_sub_f32_e32 v137, v140, v136
	v_mul_f32_e32 v137, 0x3e38aa3b, v137
	v_exp_f32_e32 v137, v137
	s_cmp_eq_u64 vcc, exec
	s_cselect_b64 s[4:5], -1, 0
	s_barrier
	s_waitcnt vmcnt(3)
	v_cndmask_b32_e64 v192, v137, 1.0, s[4:5]
	v_cmp_gt_f32_e32 vcc, 1.0, v192
	s_waitcnt vmcnt(3)
	ds_write_b128 v179, v[112:115]
	ds_write_b128 v180, v[116:119]
	ds_write_b128 v186, v[120:123] offset:32768
	s_cbranch_vccz .LBB0_1089
	s_and_saveexec_b64 s[8:9], s[6:7]
	ds_write_b32 v155, v192 offset:49280
	s_or_b64 exec, exec, s[8:9]
	s_waitcnt lgkmcnt(0)
	v_add_u32_e32 v137, v153, v178
	ds_read_b128 v[142:145], v137 offset:49376
	ds_read_b128 v[146:149], v137 offset:49344
	ds_read_b128 v[194:197], v137 offset:49312
	ds_read_b128 v[198:201], v137 offset:49280
	s_waitcnt lgkmcnt(3)
	v_pk_mul_f32 v[12:13], v[12:13], v[142:143]
	s_waitcnt lgkmcnt(2)
	v_pk_mul_f32 v[8:9], v[8:9], v[146:147]
	s_waitcnt lgkmcnt(1)
	v_pk_mul_f32 v[4:5], v[4:5], v[194:195]
	v_pk_mul_f32 v[14:15], v[14:15], v[144:145]
	v_pk_mul_f32 v[10:11], v[10:11], v[148:149]
	v_pk_mul_f32 v[6:7], v[6:7], v[196:197]
	s_waitcnt lgkmcnt(0)
	v_pk_mul_f32 v[2:3], v[2:3], v[200:201]
	v_pk_mul_f32 v[0:1], v[0:1], v[198:199]
	v_pk_mul_f32 v[60:61], v[60:61], v[142:143]
	v_pk_mul_f32 v[56:57], v[56:57], v[146:147]
	v_pk_mul_f32 v[52:53], v[52:53], v[194:195]
	v_pk_mul_f32 v[62:63], v[62:63], v[144:145]
	v_pk_mul_f32 v[58:59], v[58:59], v[148:149]
	v_pk_mul_f32 v[54:55], v[54:55], v[196:197]
	v_pk_mul_f32 v[50:51], v[50:51], v[200:201]
	v_pk_mul_f32 v[48:49], v[48:49], v[198:199]
	v_pk_mul_f32 v[44:45], v[44:45], v[142:143]
	v_pk_mul_f32 v[40:41], v[40:41], v[146:147]
	v_pk_mul_f32 v[36:37], v[36:37], v[194:195]
	v_pk_mul_f32 v[46:47], v[46:47], v[144:145]
	v_pk_mul_f32 v[42:43], v[42:43], v[148:149]
	v_pk_mul_f32 v[38:39], v[38:39], v[196:197]
	v_pk_mul_f32 v[34:35], v[34:35], v[200:201]
	v_pk_mul_f32 v[32:33], v[32:33], v[198:199]
	v_pk_mul_f32 v[28:29], v[28:29], v[142:143]
	v_pk_mul_f32 v[24:25], v[24:25], v[146:147]
	v_pk_mul_f32 v[20:21], v[20:21], v[194:195]
	v_pk_mul_f32 v[30:31], v[30:31], v[144:145]
	v_pk_mul_f32 v[26:27], v[26:27], v[148:149]
	v_pk_mul_f32 v[22:23], v[22:23], v[196:197]
	v_pk_mul_f32 v[18:19], v[18:19], v[200:201]
	v_pk_mul_f32 v[16:17], v[16:17], v[198:199]

.LBB0_1091:
	ds_read_b64_tr_b16 v[160:161], v174 offset:0
	ds_read_b64_tr_b16 v[162:163], v174 offset:0x800
	ds_read_b64_tr_b16 v[196:197], v174 offset:0x1000
	ds_read_b64_tr_b16 v[198:199], v174 offset:0x1800
	ds_read_b64_tr_b16 v[200:201], v174 offset:0x2000
	ds_read_b64_tr_b16 v[202:203], v174 offset:0x2800
	ds_read_b64_tr_b16 v[204:205], v174 offset:0x3000
	ds_read_b64_tr_b16 v[206:207], v174 offset:0x3800
	s_waitcnt lgkmcnt(0)
	s_nop 0
	v_mfma_f32_32x32x16_bf16 v[0:15], v[136:139], v[160:163], v[0:15]
	ds_read_b64_tr_b16 v[160:161], v174 offset:0x200
	ds_read_b64_tr_b16 v[162:163], v174 offset:0xa00
	v_mfma_f32_32x32x16_bf16 v[0:15], v[140:143], v[196:199], v[0:15]
	ds_read_b64_tr_b16 v[196:197], v174 offset:0x1200
	ds_read_b64_tr_b16 v[198:199], v174 offset:0x1a00
	v_mfma_f32_32x32x16_bf16 v[0:15], v[144:147], v[200:203], v[0:15]
	ds_read_b64_tr_b16 v[200:201], v174 offset:0x2200
	ds_read_b64_tr_b16 v[202:203], v174 offset:0x2a00
	v_mfma_f32_32x32x16_bf16 v[0:15], v[148:151], v[204:207], v[0:15]
	ds_read_b64_tr_b16 v[204:205], v174 offset:0x3200
	ds_read_b64_tr_b16 v[206:207], v174 offset:0x3a00
	s_waitcnt lgkmcnt(0)
	v_mfma_f32_32x32x16_bf16 v[48:63], v[136:139], v[160:163], v[48:63]
	ds_read_b64_tr_b16 v[160:161], v174 offset:0x400
	ds_read_b64_tr_b16 v[162:163], v174 offset:0xc00
	v_mfma_f32_32x32x16_bf16 v[48:63], v[140:143], v[196:199], v[48:63]
	ds_read_b64_tr_b16 v[196:197], v174 offset:0x1400
	ds_read_b64_tr_b16 v[198:199], v174 offset:0x1c00
	v_mfma_f32_32x32x16_bf16 v[48:63], v[144:147], v[200:203], v[48:63]
	ds_read_b64_tr_b16 v[200:201], v174 offset:0x2400
	ds_read_b64_tr_b16 v[202:203], v174 offset:0x2c00
	v_mfma_f32_32x32x16_bf16 v[48:63], v[148:151], v[204:207], v[48:63]
	ds_read_b64_tr_b16 v[204:205], v174 offset:0x3400
	ds_read_b64_tr_b16 v[206:207], v174 offset:0x3c00
	s_waitcnt lgkmcnt(0)
	v_mfma_f32_32x32x16_bf16 v[32:47], v[136:139], v[160:163], v[32:47]
	ds_read_b64_tr_b16 v[160:161], v174 offset:0x600
	ds_read_b64_tr_b16 v[162:163], v174 offset:0xe00
	v_mfma_f32_32x32x16_bf16 v[32:47], v[140:143], v[196:199], v[32:47]
	ds_read_b64_tr_b16 v[196:197], v174 offset:0x1600
	ds_read_b64_tr_b16 v[198:199], v174 offset:0x1e00
	v_mfma_f32_32x32x16_bf16 v[32:47], v[144:147], v[200:203], v[32:47]
	ds_read_b64_tr_b16 v[200:201], v174 offset:0x2600
	ds_read_b64_tr_b16 v[202:203], v174 offset:0x2e00
	v_mfma_f32_32x32x16_bf16 v[32:47], v[148:151], v[204:207], v[32:47]
	ds_read_b64_tr_b16 v[204:205], v174 offset:0x3600
	ds_read_b64_tr_b16 v[206:207], v174 offset:0x3e00
	s_waitcnt lgkmcnt(0)
	v_mfma_f32_32x32x16_bf16 v[16:31], v[136:139], v[160:163], v[16:31]
	v_max_f32_e32 v136, v80, v81
	v_max3_f32 v136, v136, v82, v83
	v_max3_f32 v136, v136, v84, v85
	v_max3_f32 v136, v136, v86, v87
	v_max3_f32 v136, v136, v88, v89
	v_max3_f32 v136, v136, v90, v91
	v_max3_f32 v136, v136, v92, v93
	v_mfma_f32_32x32x16_bf16 v[16:31], v[140:143], v[196:199], v[16:31]
	v_max3_f32 v136, v136, v94, v95
	v_max3_f32 v136, v136, v64, v65
	v_max3_f32 v136, v136, v66, v67
	v_max3_f32 v136, v136, v68, v69
	v_max3_f32 v136, v136, v70, v71
	v_max3_f32 v136, v136, v72, v73
	v_max3_f32 v136, v136, v74, v75
	v_max3_f32 v136, v136, v76, v77
	v_mfma_f32_32x32x16_bf16 v[16:31], v[144:147], v[200:203], v[16:31]
	v_max3_f32 v136, v136, v78, v79
	v_mov_b32_e32 v137, v136
	s_nop 1
	v_permlane32_swap_b32_e32 v136, v137
	v_max_f32_e32 v137, v137, v137
	v_max_f32_e32 v136, v136, v136
	v_max_f32_e32 v136, v136, v137
	v_sub_f32_e32 v137, v136, v193
	v_cmp_ge_f32_e32 vcc, s38, v137
	v_max_f32_e32 v136, v193, v136
	v_mfma_f32_32x32x16_bf16 v[16:31], v[148:151], v[204:207], v[16:31]
	v_sub_f32_e32 v137, v193, v136
	v_mul_f32_e32 v137, 0x3e38aa3b, v137
	v_exp_f32_e32 v137, v137
	s_cmp_eq_u64 vcc, exec
	s_cselect_b64 s[4:5], -1, 0
	s_barrier
	s_waitcnt vmcnt(3)
	v_cndmask_b32_e64 v141, v137, 1.0, s[4:5]
	v_cmp_gt_f32_e32 vcc, 1.0, v141
	s_cmp_lg_u64 s[8:9], 0
	s_cbranch_scc0 .Lsw_da
	s_waitcnt vmcnt(0)
